# grid barrier re-written by hand in 28 of its 29 inlined instances: XCD arrival counter, then every workgroup polls the top counter directly (no generation-word hops)
# baseline (speedup 1.0000x reference)
.LBB0_206:
	s_waitcnt vmcnt(0)
	s_waitcnt vmcnt(0)
	s_barrier
	s_mov_b64 s[4:5], exec
	v_readlane_b32 s0, v254, 3
	v_readlane_b32 s1, v254, 4
	s_and_b64 s[0:1], s[4:5], s[0:1]
	s_mov_b64 exec, s[0:1]
	s_cbranch_execz .LBB0_258
	v_mov_b32_e32 v4, 0x240c0
	s_waitcnt vmcnt(0) lgkmcnt(0)
	ds_read_b32 v5, v4
	ds_read_b32 v6, v4 offset:4
	v_readlane_b32 s0, v254, 2
	s_waitcnt lgkmcnt(0)
	v_readfirstlane_b32 s1, v5
	v_readfirstlane_b32 s2, v6
	s_lshl_b32 s0, s0, 8
	s_add_i32 s0, s0, 0xc605400
	v_mov_b32_e32 v4, s0
	v_mov_b32_e32 v5, 1
	global_atomic_add v6, v4, v5, s[38:39] sc0
	v_cvt_f32_u32_e32 v4, s1
	v_rcp_f32_e32 v4, v4
	s_waitcnt vmcnt(0)
	v_cvt_f32_u32_e32 v5, v6
	v_add_f32_e32 v5, 0.5, v5
	v_mul_f32_e32 v5, v5, v4
	v_cvt_u32_f32_e32 v5, v5
	v_readfirstlane_b32 s7, v6
	v_readfirstlane_b32 s3, v5
	s_add_i32 s7, s7, 1
	s_add_i32 s3, s3, 1
	s_mul_i32 s6, s3, s1
	s_mul_i32 s3, s3, s2
	s_cmp_lg_u32 s7, s6
	s_cbranch_scc1 .Lfb_nl_1
	buffer_wbl2 sc1
	s_waitcnt vmcnt(0)
	v_mov_b32_e32 v4, 0xc607400
	v_mov_b32_e32 v5, 1
	global_atomic_add v4, v5, s[38:39]
.Lfb_nl_1:
	v_mov_b32_e32 v4, 0xc607400
	s_mov_b32 s7, 0
.Lfb_sp_1:
	global_load_dword v6, v4, s[38:39] sc1
	s_waitcnt vmcnt(0)
	v_readfirstlane_b32 s6, v6
	s_cmp_ge_u32 s6, s3
	s_cbranch_scc1 .Lfb_dn_1
	s_sleep 1
	s_add_i32 s7, s7, 1
	s_cmp_lt_u32 s7, 0x8000
	s_cbranch_scc1 .Lfb_sp_1
.Lfb_dn_1:
	buffer_inv sc1
	s_waitcnt vmcnt(0)

.LBB0_353:
	s_waitcnt vmcnt(0)
	s_waitcnt lgkmcnt(0)
	s_barrier
	s_mov_b64 s[4:5], exec
	v_readlane_b32 s0, v254, 3
	v_readlane_b32 s1, v254, 4
	s_and_b64 s[0:1], s[4:5], s[0:1]
	s_mov_b64 exec, s[0:1]
	s_cbranch_execz .LBB0_405
	v_mov_b32_e32 v0, 0x240c0
	s_waitcnt vmcnt(0) lgkmcnt(0)
	ds_read_b32 v4, v0
	ds_read_b32 v5, v0 offset:4
	v_readlane_b32 s0, v254, 2
	s_waitcnt lgkmcnt(0)
	v_readfirstlane_b32 s1, v4
	v_readfirstlane_b32 s2, v5
	s_lshl_b32 s0, s0, 8
	s_add_i32 s0, s0, 0xc605400
	v_mov_b32_e32 v0, s0
	v_mov_b32_e32 v4, 1
	global_atomic_add v5, v0, v4, s[38:39] sc0
	v_cvt_f32_u32_e32 v0, s1
	v_rcp_f32_e32 v0, v0
	s_waitcnt vmcnt(0)
	v_cvt_f32_u32_e32 v4, v5
	v_add_f32_e32 v4, 0.5, v4
	v_mul_f32_e32 v4, v4, v0
	v_cvt_u32_f32_e32 v4, v4
	v_readfirstlane_b32 s7, v5
	v_readfirstlane_b32 s3, v4
	s_add_i32 s7, s7, 1
	s_add_i32 s3, s3, 1
	s_mul_i32 s6, s3, s1
	s_mul_i32 s3, s3, s2
	s_cmp_lg_u32 s7, s6
	s_cbranch_scc1 .Lfb_nl_2
	buffer_wbl2 sc1
	s_waitcnt vmcnt(0)
	v_mov_b32_e32 v0, 0xc607400
	v_mov_b32_e32 v4, 1
	global_atomic_add v0, v4, s[38:39]
.Lfb_nl_2:
	v_mov_b32_e32 v0, 0xc607400
	s_mov_b32 s7, 0
.Lfb_sp_2:
	global_load_dword v5, v0, s[38:39] sc1
	s_waitcnt vmcnt(0)
	v_readfirstlane_b32 s6, v5
	s_cmp_ge_u32 s6, s3
	s_cbranch_scc1 .Lfb_dn_2
	s_sleep 1
	s_add_i32 s7, s7, 1
	s_cmp_lt_u32 s7, 0x8000
	s_cbranch_scc1 .Lfb_sp_2

.LBB0_429:
	s_waitcnt vmcnt(0)
	s_barrier
	s_mov_b64 s[4:5], exec
	v_readlane_b32 s0, v254, 3
	v_readlane_b32 s1, v254, 4
	s_and_b64 s[0:1], s[4:5], s[0:1]
	s_mov_b64 exec, s[0:1]
	s_cbranch_execz .LBB0_481
	v_mov_b32_e32 v0, 0x240c0
	s_waitcnt vmcnt(0) lgkmcnt(0)
	ds_read_b32 v4, v0
	ds_read_b32 v5, v0 offset:4
	v_readlane_b32 s0, v254, 2
	s_waitcnt lgkmcnt(0)
	v_readfirstlane_b32 s1, v4
	v_readfirstlane_b32 s2, v5
	s_lshl_b32 s0, s0, 8
	s_add_i32 s0, s0, 0xc605400
	v_mov_b32_e32 v0, s0
	v_mov_b32_e32 v4, 1
	global_atomic_add v5, v0, v4, s[38:39] sc0
	v_cvt_f32_u32_e32 v0, s1
	v_rcp_f32_e32 v0, v0
	s_waitcnt vmcnt(0)
	v_cvt_f32_u32_e32 v4, v5
	v_add_f32_e32 v4, 0.5, v4
	v_mul_f32_e32 v4, v4, v0
	v_cvt_u32_f32_e32 v4, v4
	v_readfirstlane_b32 s9, v5
	v_readfirstlane_b32 s3, v4
	s_add_i32 s9, s9, 1
	s_add_i32 s3, s3, 1
	s_mul_i32 s8, s3, s1
	s_mul_i32 s3, s3, s2
	s_cmp_lg_u32 s9, s8
	s_cbranch_scc1 .Lfb_nl_3
	buffer_wbl2 sc1
	s_waitcnt vmcnt(0)
	v_mov_b32_e32 v0, 0xc607400
	v_mov_b32_e32 v4, 1
	global_atomic_add v0, v4, s[38:39]
.Lfb_nl_3:
	v_mov_b32_e32 v0, 0xc607400
	s_mov_b32 s9, 0
.Lfb_sp_3:
	global_load_dword v5, v0, s[38:39] sc1
	s_waitcnt vmcnt(0)
	v_readfirstlane_b32 s8, v5
	s_cmp_ge_u32 s8, s3
	s_cbranch_scc1 .Lfb_dn_3
	s_sleep 1
	s_add_i32 s9, s9, 1
	s_cmp_lt_u32 s9, 0x8000
	s_cbranch_scc1 .Lfb_sp_3

.LBB0_562:
	s_waitcnt vmcnt(0)
	s_waitcnt vmcnt(0)
	s_barrier
	s_mov_b64 s[4:5], exec
	v_readlane_b32 s0, v254, 3
	v_readlane_b32 s1, v254, 4
	s_and_b64 s[0:1], s[4:5], s[0:1]
	s_mov_b64 exec, s[0:1]
	s_cbranch_execz .LBB0_614
	v_mov_b32_e32 v0, 0x240c0
	s_waitcnt vmcnt(0) lgkmcnt(0)
	ds_read_b32 v4, v0
	ds_read_b32 v5, v0 offset:4
	v_readlane_b32 s0, v254, 2
	s_waitcnt lgkmcnt(0)
	v_readfirstlane_b32 s1, v4
	v_readfirstlane_b32 s2, v5
	s_lshl_b32 s0, s0, 8
	s_add_i32 s0, s0, 0xc605400
	v_mov_b32_e32 v0, s0
	v_mov_b32_e32 v4, 1
	global_atomic_add v5, v0, v4, s[38:39] sc0
	v_cvt_f32_u32_e32 v0, s1
	v_rcp_f32_e32 v0, v0
	s_waitcnt vmcnt(0)
	v_cvt_f32_u32_e32 v4, v5
	v_add_f32_e32 v4, 0.5, v4
	v_mul_f32_e32 v4, v4, v0
	v_cvt_u32_f32_e32 v4, v4
	v_readfirstlane_b32 s9, v5
	v_readfirstlane_b32 s3, v4
	s_add_i32 s9, s9, 1
	s_add_i32 s3, s3, 1
	s_mul_i32 s8, s3, s1
	s_mul_i32 s3, s3, s2
	s_cmp_lg_u32 s9, s8
	s_cbranch_scc1 .Lfb_nl_5
	buffer_wbl2 sc1
	s_waitcnt vmcnt(0)
	v_mov_b32_e32 v0, 0xc607400
	v_mov_b32_e32 v4, 1
	global_atomic_add v0, v4, s[38:39]

.LBB0_638:
	s_waitcnt vmcnt(0)
	s_barrier
	s_mov_b64 s[6:7], exec
	v_readlane_b32 s0, v254, 3
	v_readlane_b32 s1, v254, 4
	s_and_b64 s[0:1], s[6:7], s[0:1]
	s_mov_b64 exec, s[0:1]
	s_cbranch_execz .LBB0_690
	v_mov_b32_e32 v0, 0x240c0
	s_waitcnt vmcnt(0) lgkmcnt(0)
	ds_read_b32 v4, v0
	ds_read_b32 v5, v0 offset:4
	v_readlane_b32 s0, v254, 2
	s_waitcnt lgkmcnt(0)
	v_readfirstlane_b32 s1, v4
	v_readfirstlane_b32 s2, v5
	s_lshl_b32 s0, s0, 8
	s_add_i32 s0, s0, 0xc605400
	v_mov_b32_e32 v0, s0
	v_mov_b32_e32 v4, 1
	global_atomic_add v5, v0, v4, s[38:39] sc0
	v_cvt_f32_u32_e32 v0, s1
	v_rcp_f32_e32 v0, v0
	s_waitcnt vmcnt(0)
	v_cvt_f32_u32_e32 v4, v5
	v_add_f32_e32 v4, 0.5, v4
	v_mul_f32_e32 v4, v4, v0
	v_cvt_u32_f32_e32 v4, v4
	v_readfirstlane_b32 s5, v5
	v_readfirstlane_b32 s3, v4
	s_add_i32 s5, s5, 1
	s_add_i32 s3, s3, 1
	s_mul_i32 s4, s3, s1
	s_mul_i32 s3, s3, s2
	s_cmp_lg_u32 s5, s4
	s_cbranch_scc1 .Lfb_nl_6
	buffer_wbl2 sc1
	s_waitcnt vmcnt(0)
	v_mov_b32_e32 v0, 0xc607400
	v_mov_b32_e32 v4, 1
	global_atomic_add v0, v4, s[38:39]
.Lfb_nl_6:
	v_mov_b32_e32 v0, 0xc607400
	s_mov_b32 s5, 0
.Lfb_sp_6:
	global_load_dword v5, v0, s[38:39] sc1
	s_waitcnt vmcnt(0)
	v_readfirstlane_b32 s4, v5
	s_cmp_ge_u32 s4, s3
	s_cbranch_scc1 .Lfb_dn_6
	s_sleep 1
	s_add_i32 s5, s5, 1
	s_cmp_lt_u32 s5, 0x8000
	s_cbranch_scc1 .Lfb_sp_6

.LBB0_754:
	s_waitcnt vmcnt(0)
	s_waitcnt lgkmcnt(0)
	s_barrier
	s_mov_b64 s[6:7], exec
	v_readlane_b32 s0, v254, 3
	v_readlane_b32 s1, v254, 4
	s_and_b64 s[0:1], s[6:7], s[0:1]
	s_mov_b64 exec, s[0:1]
	s_cbranch_execz .LBB0_806
	v_mov_b32_e32 v0, 0x240c0
	s_waitcnt vmcnt(0) lgkmcnt(0)
	ds_read_b32 v4, v0
	ds_read_b32 v5, v0 offset:4
	v_readlane_b32 s0, v254, 2
	s_waitcnt lgkmcnt(0)
	v_readfirstlane_b32 s1, v4
	v_readfirstlane_b32 s2, v5
	s_lshl_b32 s0, s0, 8
	s_add_i32 s0, s0, 0xc605400
	v_mov_b32_e32 v0, s0
	v_mov_b32_e32 v4, 1
	global_atomic_add v5, v0, v4, s[38:39] sc0
	v_cvt_f32_u32_e32 v0, s1
	v_rcp_f32_e32 v0, v0
	s_waitcnt vmcnt(0)
	v_cvt_f32_u32_e32 v4, v5
	v_add_f32_e32 v4, 0.5, v4
	v_mul_f32_e32 v4, v4, v0
	v_cvt_u32_f32_e32 v4, v4
	v_readfirstlane_b32 s5, v5
	v_readfirstlane_b32 s3, v4
	s_add_i32 s5, s5, 1
	s_add_i32 s3, s3, 1
	s_mul_i32 s4, s3, s1
	s_mul_i32 s3, s3, s2
	s_cmp_lg_u32 s5, s4
	s_cbranch_scc1 .Lfb_nl_7
	buffer_wbl2 sc1
	s_waitcnt vmcnt(0)
	v_mov_b32_e32 v0, 0xc607400
	v_mov_b32_e32 v4, 1
	global_atomic_add v0, v4, s[38:39]

.LBB0_835:
	s_or_b64 exec, exec, s[6:7]
	s_waitcnt vmcnt(0)
	s_barrier
	s_mov_b64 s[6:7], exec
	v_readlane_b32 s0, v254, 3
	v_readlane_b32 s1, v254, 4
	s_and_b64 s[0:1], s[6:7], s[0:1]
	s_mov_b64 exec, s[0:1]
	s_cbranch_execz .LBB0_887
	v_mov_b32_e32 v0, 0x240c0
	s_waitcnt vmcnt(0) lgkmcnt(0)
	ds_read_b32 v1, v0
	ds_read_b32 v4, v0 offset:4
	v_readlane_b32 s0, v254, 2
	s_waitcnt lgkmcnt(0)
	v_readfirstlane_b32 s1, v1
	v_readfirstlane_b32 s2, v4
	s_lshl_b32 s0, s0, 8
	s_add_i32 s0, s0, 0xc605400
	v_mov_b32_e32 v0, s0
	v_mov_b32_e32 v1, 1
	global_atomic_add v4, v0, v1, s[38:39] sc0
	v_cvt_f32_u32_e32 v0, s1
	v_rcp_f32_e32 v0, v0
	s_waitcnt vmcnt(0)
	v_cvt_f32_u32_e32 v1, v4
	v_add_f32_e32 v1, 0.5, v1
	v_mul_f32_e32 v1, v1, v0
	v_cvt_u32_f32_e32 v1, v1
	v_readfirstlane_b32 s5, v4
	v_readfirstlane_b32 s3, v1
	s_add_i32 s5, s5, 1
	s_add_i32 s3, s3, 1
	s_mul_i32 s4, s3, s1
	s_mul_i32 s3, s3, s2
	s_cmp_lg_u32 s5, s4
	s_cbranch_scc1 .Lfb_nl_8
	buffer_wbl2 sc1
	s_waitcnt vmcnt(0)
	v_mov_b32_e32 v0, 0xc607400
	v_mov_b32_e32 v1, 1
	global_atomic_add v0, v1, s[38:39]

.Lfb_sp_8:
	global_load_dword v4, v0, s[38:39] sc1
	s_waitcnt vmcnt(0)
	v_readfirstlane_b32 s4, v4
	s_cmp_ge_u32 s4, s3
	s_cbranch_scc1 .Lfb_dn_8
	s_sleep 1
	s_add_i32 s5, s5, 1
	s_cmp_lt_u32 s5, 0x8000
	s_cbranch_scc1 .Lfb_sp_8

.LBB0_925:
	s_waitcnt vmcnt(0)
	s_waitcnt lgkmcnt(0)
	s_barrier
	s_mov_b64 s[6:7], exec
	v_readlane_b32 s0, v254, 3
	v_readlane_b32 s1, v254, 4
	s_and_b64 s[0:1], s[6:7], s[0:1]
	s_mov_b64 exec, s[0:1]
	s_cbranch_execz .LBB0_977
	v_mov_b32_e32 v0, 0x240c0
	s_waitcnt vmcnt(0) lgkmcnt(0)
	ds_read_b32 v1, v0
	ds_read_b32 v4, v0 offset:4
	v_readlane_b32 s0, v254, 2
	s_waitcnt lgkmcnt(0)
	v_readfirstlane_b32 s1, v1
	v_readfirstlane_b32 s2, v4
	s_lshl_b32 s0, s0, 8
	s_add_i32 s0, s0, 0xc605400
	v_mov_b32_e32 v0, s0
	v_mov_b32_e32 v1, 1
	global_atomic_add v4, v0, v1, s[38:39] sc0
	v_cvt_f32_u32_e32 v0, s1
	v_rcp_f32_e32 v0, v0
	s_waitcnt vmcnt(0)
	v_cvt_f32_u32_e32 v1, v4
	v_add_f32_e32 v1, 0.5, v1
	v_mul_f32_e32 v1, v1, v0
	v_cvt_u32_f32_e32 v1, v1
	v_readfirstlane_b32 s5, v4
	v_readfirstlane_b32 s3, v1
	s_add_i32 s5, s5, 1
	s_add_i32 s3, s3, 1
	s_mul_i32 s4, s3, s1
	s_mul_i32 s3, s3, s2
	s_cmp_lg_u32 s5, s4
	s_cbranch_scc1 .Lfb_nl_9
	buffer_wbl2 sc1
	s_waitcnt vmcnt(0)
	v_mov_b32_e32 v0, 0xc607400
	v_mov_b32_e32 v1, 1
	global_atomic_add v0, v1, s[38:39]

.LBB0_982:
	s_waitcnt vmcnt(0)
	s_barrier
	s_mov_b64 s[6:7], exec
	v_readlane_b32 s0, v254, 3
	v_readlane_b32 s1, v254, 4
	s_and_b64 s[0:1], s[6:7], s[0:1]
	s_mov_b64 exec, s[0:1]
	s_cbranch_execz .LBB0_1034
	v_mov_b32_e32 v0, 0x240c0
	s_waitcnt vmcnt(0) lgkmcnt(0)
	ds_read_b32 v1, v0
	ds_read_b32 v4, v0 offset:4
	v_readlane_b32 s0, v254, 2
	s_waitcnt lgkmcnt(0)
	v_readfirstlane_b32 s1, v1
	v_readfirstlane_b32 s2, v4
	s_lshl_b32 s0, s0, 8
	s_add_i32 s0, s0, 0xc605400
	v_mov_b32_e32 v0, s0
	v_mov_b32_e32 v1, 1
	global_atomic_add v4, v0, v1, s[38:39] sc0
	v_cvt_f32_u32_e32 v0, s1
	v_rcp_f32_e32 v0, v0
	s_waitcnt vmcnt(0)
	v_cvt_f32_u32_e32 v1, v4
	v_add_f32_e32 v1, 0.5, v1
	v_mul_f32_e32 v1, v1, v0
	v_cvt_u32_f32_e32 v1, v1
	v_readfirstlane_b32 s5, v4
	v_readfirstlane_b32 s3, v1
	s_add_i32 s5, s5, 1
	s_add_i32 s3, s3, 1
	s_mul_i32 s4, s3, s1
	s_mul_i32 s3, s3, s2
	s_cmp_lg_u32 s5, s4
	s_cbranch_scc1 .Lfb_nl_10
	buffer_wbl2 sc1
	s_waitcnt vmcnt(0)
	v_mov_b32_e32 v0, 0xc607400
	v_mov_b32_e32 v1, 1
	global_atomic_add v0, v1, s[38:39]

.LBB0_1058:
	s_waitcnt vmcnt(0)
	s_waitcnt vmcnt(0)
	s_barrier
	s_mov_b64 s[8:9], exec
	v_readlane_b32 s0, v254, 3
	v_readlane_b32 s1, v254, 4
	s_and_b64 s[0:1], s[8:9], s[0:1]
	s_mov_b64 exec, s[0:1]
	s_cbranch_execz .LBB0_1110
	v_mov_b32_e32 v0, 0x240c0
	s_waitcnt vmcnt(0) lgkmcnt(0)
	ds_read_b32 v1, v0
	ds_read_b32 v4, v0 offset:4
	v_readlane_b32 s0, v254, 2
	s_waitcnt lgkmcnt(0)
	v_readfirstlane_b32 s1, v1
	v_readfirstlane_b32 s2, v4
	s_lshl_b32 s0, s0, 8
	s_add_i32 s0, s0, 0xc605400
	v_mov_b32_e32 v0, s0
	v_mov_b32_e32 v1, 1
	global_atomic_add v4, v0, v1, s[38:39] sc0
	v_cvt_f32_u32_e32 v0, s1
	v_rcp_f32_e32 v0, v0
	s_waitcnt vmcnt(0)
	v_cvt_f32_u32_e32 v1, v4
	v_add_f32_e32 v1, 0.5, v1
	v_mul_f32_e32 v1, v1, v0
	v_cvt_u32_f32_e32 v1, v1
	v_readfirstlane_b32 s5, v4
	v_readfirstlane_b32 s3, v1
	s_add_i32 s5, s5, 1
	s_add_i32 s3, s3, 1
	s_mul_i32 s4, s3, s1
	s_mul_i32 s3, s3, s2
	s_cmp_lg_u32 s5, s4
	s_cbranch_scc1 .Lfb_nl_11
	buffer_wbl2 sc1
	s_waitcnt vmcnt(0)
	v_mov_b32_e32 v0, 0xc607400
	v_mov_b32_e32 v1, 1
	global_atomic_add v0, v1, s[38:39]

.LBB0_1134:
	s_waitcnt vmcnt(0)
	s_barrier
	s_mov_b64 s[8:9], exec
	v_readlane_b32 s0, v254, 3
	v_readlane_b32 s1, v254, 4
	s_and_b64 s[0:1], s[8:9], s[0:1]
	s_mov_b64 exec, s[0:1]
	s_cbranch_execz .LBB0_1186
	v_mov_b32_e32 v0, 0x240c0
	s_waitcnt vmcnt(0) lgkmcnt(0)
	ds_read_b32 v1, v0
	ds_read_b32 v4, v0 offset:4
	v_readlane_b32 s0, v254, 2
	s_waitcnt lgkmcnt(0)
	v_readfirstlane_b32 s1, v1
	v_readfirstlane_b32 s2, v4
	s_lshl_b32 s0, s0, 8
	s_add_i32 s0, s0, 0xc605400
	v_mov_b32_e32 v0, s0
	v_mov_b32_e32 v1, 1
	global_atomic_add v4, v0, v1, s[38:39] sc0
	v_cvt_f32_u32_e32 v0, s1
	v_rcp_f32_e32 v0, v0
	s_waitcnt vmcnt(0)
	v_cvt_f32_u32_e32 v1, v4
	v_add_f32_e32 v1, 0.5, v1
	v_mul_f32_e32 v1, v1, v0
	v_cvt_u32_f32_e32 v1, v1
	v_readfirstlane_b32 s5, v4
	v_readfirstlane_b32 s3, v1
	s_add_i32 s5, s5, 1
	s_add_i32 s3, s3, 1
	s_mul_i32 s4, s3, s1
	s_mul_i32 s3, s3, s2
	s_cmp_lg_u32 s5, s4
	s_cbranch_scc1 .Lfb_nl_12
	buffer_wbl2 sc1
	s_waitcnt vmcnt(0)
	v_mov_b32_e32 v0, 0xc607400
	v_mov_b32_e32 v1, 1
	global_atomic_add v0, v1, s[38:39]

.LBB0_1409:
	s_or_b64 exec, exec, s[10:11]
	s_waitcnt vmcnt(0)
	s_waitcnt lgkmcnt(0)
	s_barrier
	s_mov_b64 s[8:9], exec
	v_readlane_b32 s0, v254, 3
	v_readlane_b32 s1, v254, 4
	s_and_b64 s[0:1], s[8:9], s[0:1]
	s_mov_b64 exec, s[0:1]
	s_cbranch_execz .LBB0_1463
	v_mov_b32_e32 v0, 0x240c0
	s_waitcnt vmcnt(0) lgkmcnt(0)
	ds_read_b32 v1, v0
	ds_read_b32 v4, v0 offset:4
	v_readlane_b32 s0, v254, 2
	s_waitcnt lgkmcnt(0)
	v_readfirstlane_b32 s1, v1
	v_readfirstlane_b32 s2, v4
	s_lshl_b32 s0, s0, 8
	s_add_i32 s0, s0, 0xc605400
	v_mov_b32_e32 v0, s0
	v_mov_b32_e32 v1, 1
	global_atomic_add v4, v0, v1, s[38:39] sc0
	v_cvt_f32_u32_e32 v0, s1
	v_rcp_f32_e32 v0, v0
	s_waitcnt vmcnt(0)
	v_cvt_f32_u32_e32 v1, v4
	v_add_f32_e32 v1, 0.5, v1
	v_mul_f32_e32 v1, v1, v0
	v_cvt_u32_f32_e32 v1, v1
	v_readfirstlane_b32 s5, v4
	v_readfirstlane_b32 s3, v1
	s_add_i32 s5, s5, 1
	s_add_i32 s3, s3, 1
	s_mul_i32 s4, s3, s1
	s_mul_i32 s3, s3, s2
	s_cmp_lg_u32 s5, s4
	s_cbranch_scc1 .Lfb_nl_15
	buffer_wbl2 sc1
	s_waitcnt vmcnt(0)
	v_mov_b32_e32 v0, 0xc607400
	v_mov_b32_e32 v1, 1
	global_atomic_add v0, v1, s[38:39]

.Lfb_dn_15:
	buffer_inv sc1
	s_waitcnt vmcnt(0)
	s_branch .LBB0_1463

.LBB0_1421:
	v_add_u32_e32 v1, -1, v0
	s_movk_i32 s0, 0x1800
	v_mov_b64_e32 v[16:17], s[38:39]
	v_mad_u64_u32 v[16:17], s[0:1], v1, s0, v[16:17]
	v_mov_b32_e32 v3, 0
	v_lshl_add_u64 v[20:21], v[16:17], 0, v[2:3]
	global_load_dwordx4 v[16:19], v[20:21], off offset:2048
	v_add_co_u32_e32 v20, vcc, 0x1000, v20
	s_mov_b64 s[0:1], 0x1000
	s_nop 0
	v_addc_co_u32_e32 v21, vcc, 0, v21, vcc
	global_load_dwordx4 v[20:23], v[20:21], off
	v_add_co_u32_e32 v28, vcc, 0x1000, v12
	v_lshl_add_u64 v[24:25], v[12:13], 0, s[0:1]
	s_nop 0
	v_addc_co_u32_e32 v29, vcc, 0, v13, vcc
	global_load_dwordx4 v[24:27], v[24:25], off offset:16
	s_nop 0
	global_load_dwordx4 v[28:31], v[28:29], off
	s_waitcnt vmcnt(3)
	v_lshlrev_b32_e32 v32, 16, v19
	v_lshlrev_b32_e32 v34, 16, v16
	v_and_b32_e32 v35, 0xffff0000, v16
	v_lshlrev_b32_e32 v36, 16, v18
	v_and_b32_e32 v37, 0xffff0000, v18
	v_lshlrev_b32_e32 v16, 16, v17
	v_and_b32_e32 v17, 0xffff0000, v17
	v_and_b32_e32 v33, 0xffff0000, v19
	s_waitcnt vmcnt(2)
	v_lshlrev_b32_e32 v18, 16, v23
	v_lshlrev_b32_e32 v38, 16, v20
	v_and_b32_e32 v39, 0xffff0000, v20
	v_lshlrev_b32_e32 v40, 16, v22
	v_and_b32_e32 v41, 0xffff0000, v22
	v_lshlrev_b32_e32 v20, 16, v21
	v_and_b32_e32 v21, 0xffff0000, v21
	v_and_b32_e32 v19, 0xffff0000, v23
	v_pk_mul_f32 v[18:19], v[32:33], v[18:19]
	v_pk_mul_f32 v[16:17], v[16:17], v[20:21]
	v_pk_mul_f32 v[20:21], v[34:35], v[38:39]
	v_pk_mul_f32 v[22:23], v[36:37], v[40:41]
	s_waitcnt vmcnt(1)
	v_pk_fma_f32 v[6:7], v[26:27], v[18:19], v[6:7]
	s_waitcnt vmcnt(0)
	v_pk_fma_f32 v[8:9], v[30:31], v[16:17], v[8:9]
	v_pk_fma_f32 v[10:11], v[24:25], v[22:23], v[10:11]
	v_pk_fma_f32 v[4:5], v[28:29], v[20:21], v[4:5]
	s_or_b64 exec, exec, s[14:15]
	v_cmp_lt_i32_e32 vcc, -1, v0
	s_and_saveexec_b64 s[14:15], vcc
	s_cbranch_execnz .LBB0_1392
	s_branch .LBB0_1393
.LBB0_1463:
	s_or_b64 exec, exec, s[8:9]
	v_readlane_b32 s0, v254, 20
	v_mov_b32_e32 v8, v160
	v_readlane_b32 s1, v254, 21
	s_waitcnt lgkmcnt(0)
	s_barrier
	s_and_b64 vcc, exec, s[0:1]
	v_readfirstlane_b32 s14, v8
	s_cbranch_vccnz .LBB0_1487
	s_ashr_i32 s0, s79, 31
	s_lshr_b32 s1, s0, 29
	s_add_i32 s1, s79, s1
	s_and_b32 s2, s1, -8
	s_sub_i32 s3, s79, s2
	s_cmp_gt_i32 s3, -1
	s_cbranch_scc0 .LBB0_1466
	s_lshl_b32 s2, s3, 5
	s_cbranch_execz .LBB0_1467
	s_branch .LBB0_1468

.LBB0_1912:
	s_waitcnt vmcnt(0)
	s_waitcnt lgkmcnt(0)
	s_barrier
	s_mov_b64 s[8:9], exec
	v_readlane_b32 s0, v254, 3
	v_readlane_b32 s1, v254, 4
	s_and_b64 s[0:1], s[8:9], s[0:1]
	s_mov_b64 exec, s[0:1]
	s_cbranch_execz .LBB0_1964
	v_mov_b32_e32 v0, 0x240c0
	s_waitcnt vmcnt(0) lgkmcnt(0)
	ds_read_b32 v1, v0
	ds_read_b32 v4, v0 offset:4
	v_readlane_b32 s0, v254, 2
	s_waitcnt lgkmcnt(0)
	v_readfirstlane_b32 s1, v1
	v_readfirstlane_b32 s2, v4
	s_lshl_b32 s0, s0, 8
	s_add_i32 s0, s0, 0xc605400
	v_mov_b32_e32 v0, s0
	v_mov_b32_e32 v1, 1
	global_atomic_add v4, v0, v1, s[38:39] sc0
	v_cvt_f32_u32_e32 v0, s1
	v_rcp_f32_e32 v0, v0
	s_waitcnt vmcnt(0)
	v_cvt_f32_u32_e32 v1, v4
	v_add_f32_e32 v1, 0.5, v1
	v_mul_f32_e32 v1, v1, v0
	v_cvt_u32_f32_e32 v1, v1
	v_readfirstlane_b32 s5, v4
	v_readfirstlane_b32 s3, v1
	s_add_i32 s5, s5, 1
	s_add_i32 s3, s3, 1
	s_mul_i32 s4, s3, s1
	s_mul_i32 s3, s3, s2
	s_cmp_lg_u32 s5, s4
	s_cbranch_scc1 .Lfb_nl_20
	buffer_wbl2 sc1
	s_waitcnt vmcnt(0)
	v_mov_b32_e32 v0, 0xc607400
	v_mov_b32_e32 v1, 1
	global_atomic_add v0, v1, s[38:39]

.LBB0_2475:
	s_waitcnt vmcnt(0)
	s_waitcnt vmcnt(0) lgkmcnt(0)
	s_barrier
	s_mov_b64 s[10:11], exec
	v_readlane_b32 s0, v254, 3
	v_readlane_b32 s1, v254, 4
	s_and_b64 s[0:1], s[10:11], s[0:1]
	s_mov_b64 exec, s[0:1]
	s_cbranch_execz .LBB0_2527
	v_mov_b32_e32 v0, 0x240c0
	s_waitcnt vmcnt(0) lgkmcnt(0)
	ds_read_b32 v1, v0
	ds_read_b32 v4, v0 offset:4
	v_readlane_b32 s0, v254, 2
	s_waitcnt lgkmcnt(0)
	v_readfirstlane_b32 s1, v1
	v_readfirstlane_b32 s2, v4
	s_lshl_b32 s0, s0, 8
	s_add_i32 s0, s0, 0xc605400
	v_mov_b32_e32 v0, s0
	v_mov_b32_e32 v1, 1
	global_atomic_add v4, v0, v1, s[38:39] sc0
	v_cvt_f32_u32_e32 v0, s1
	v_rcp_f32_e32 v0, v0
	s_waitcnt vmcnt(0)
	v_cvt_f32_u32_e32 v1, v4
	v_add_f32_e32 v1, 0.5, v1
	v_mul_f32_e32 v1, v1, v0
	v_cvt_u32_f32_e32 v1, v1
	v_readfirstlane_b32 s5, v4
	v_readfirstlane_b32 s3, v1
	s_add_i32 s5, s5, 1
	s_add_i32 s3, s3, 1
	s_mul_i32 s4, s3, s1
	s_mul_i32 s3, s3, s2
	s_cmp_lg_u32 s5, s4
	s_cbranch_scc1 .Lfb_nl_21
	buffer_wbl2 sc1
	s_waitcnt vmcnt(0)
	v_mov_b32_e32 v0, 0xc607400
	v_mov_b32_e32 v1, 1
	global_atomic_add v0, v1, s[38:39]

.LBB0_3643:
	s_waitcnt vmcnt(0)
	s_waitcnt lgkmcnt(0)
	s_barrier
	s_mov_b64 s[8:9], exec
	v_readlane_b32 s2, v254, 3
	v_readlane_b32 s3, v254, 4
	v_writelane_b32 v254, s92, 30
	s_and_b64 s[2:3], s[8:9], s[2:3]
	s_nop 0
	v_writelane_b32 v254, s93, 31
	v_writelane_b32 v254, s91, 32
	s_mov_b64 exec, s[2:3]
	s_cbranch_execz .LBB0_3695
	v_mov_b32_e32 v0, 0x240c0
	s_waitcnt vmcnt(0) lgkmcnt(0)
	ds_read_b32 v1, v0
	ds_read_b32 v4, v0 offset:4
	v_readlane_b32 s1, v254, 2
	s_waitcnt lgkmcnt(0)
	v_readfirstlane_b32 s2, v1
	v_readfirstlane_b32 s3, v4
	s_lshl_b32 s1, s1, 8
	s_add_i32 s1, s1, 0xc605400
	v_mov_b32_e32 v0, s1
	v_mov_b32_e32 v1, 1
	global_atomic_add v4, v0, v1, s[38:39] sc0
	v_cvt_f32_u32_e32 v0, s2
	v_rcp_f32_e32 v0, v0
	s_waitcnt vmcnt(0)
	v_cvt_f32_u32_e32 v1, v4
	v_add_f32_e32 v1, 0.5, v1
	v_mul_f32_e32 v1, v1, v0
	v_cvt_u32_f32_e32 v1, v1
	v_readfirstlane_b32 s54, v4
	v_readfirstlane_b32 s4, v1
	s_add_i32 s54, s54, 1
	s_add_i32 s4, s4, 1
	s_mul_i32 s5, s4, s2
	s_mul_i32 s4, s4, s3
	s_cmp_lg_u32 s54, s5
	s_cbranch_scc1 .Lfb_nl_22
	buffer_wbl2 sc1
	s_waitcnt vmcnt(0)
	v_mov_b32_e32 v0, 0xc607400
	v_mov_b32_e32 v1, 1
	global_atomic_add v0, v1, s[38:39]
.Lfb_nl_22:
	v_mov_b32_e32 v0, 0xc607400
	s_mov_b32 s54, 0
.Lfb_sp_22:
	global_load_dword v4, v0, s[38:39] sc1
	s_waitcnt vmcnt(0)
	v_readfirstlane_b32 s5, v4
	s_cmp_ge_u32 s5, s4
	s_cbranch_scc1 .Lfb_dn_22
	s_sleep 1
	s_add_i32 s54, s54, 1
	s_cmp_lt_u32 s54, 0x8000
	s_cbranch_scc1 .Lfb_sp_22

.LBB0_4178:
	s_barrier
	s_waitcnt vmcnt(0)
	s_barrier
	s_mov_b64 s[8:9], exec
	v_readlane_b32 s0, v254, 3
	v_readlane_b32 s1, v254, 4
	v_readlane_b32 s72, v254, 37
	v_readlane_b32 s74, v254, 30
	s_and_b64 s[0:1], s[8:9], s[0:1]
	v_readlane_b32 s73, v254, 38
	v_readlane_b32 s75, v254, 31
	v_readlane_b32 s76, v254, 32
	v_readlane_b32 s77, v254, 8
	s_mov_b64 exec, s[0:1]
	s_cbranch_execz .LBB0_4230
	v_mov_b32_e32 v0, 0x240c0
	s_waitcnt vmcnt(0) lgkmcnt(0)
	ds_read_b32 v1, v0
	ds_read_b32 v2, v0 offset:4
	v_readlane_b32 s0, v254, 2
	s_waitcnt lgkmcnt(0)
	v_readfirstlane_b32 s1, v1
	v_readfirstlane_b32 s2, v2
	s_lshl_b32 s0, s0, 8
	s_add_i32 s0, s0, 0xc605400
	v_mov_b32_e32 v0, s0
	v_mov_b32_e32 v1, 1
	global_atomic_add v2, v0, v1, s[38:39] sc0
	v_cvt_f32_u32_e32 v0, s1
	v_rcp_f32_e32 v0, v0
	s_waitcnt vmcnt(0)
	v_cvt_f32_u32_e32 v1, v2
	v_add_f32_e32 v1, 0.5, v1
	v_mul_f32_e32 v1, v1, v0
	v_cvt_u32_f32_e32 v1, v1
	v_readfirstlane_b32 s5, v2
	v_readfirstlane_b32 s3, v1
	s_add_i32 s5, s5, 1
	s_add_i32 s3, s3, 1
	s_mul_i32 s4, s3, s1
	s_mul_i32 s3, s3, s2
	s_cmp_lg_u32 s5, s4
	s_cbranch_scc1 .Lfb_nl_24
	buffer_wbl2 sc1
	s_waitcnt vmcnt(0)
	v_mov_b32_e32 v0, 0xc607400
	v_mov_b32_e32 v1, 1
	global_atomic_add v0, v1, s[38:39]

.Lfb_sp_24:
	global_load_dword v2, v0, s[38:39] sc1
	s_waitcnt vmcnt(0)
	v_readfirstlane_b32 s4, v2
	s_cmp_ge_u32 s4, s3
	s_cbranch_scc1 .Lfb_dn_24
	s_sleep 1
	s_add_i32 s5, s5, 1
	s_cmp_lt_u32 s5, 0x8000
	s_cbranch_scc1 .Lfb_sp_24

.LBB0_4254:
	s_waitcnt vmcnt(0)
	s_barrier
	s_mov_b64 s[8:9], exec
	v_readlane_b32 s0, v254, 3
	v_readlane_b32 s1, v254, 4
	s_and_b64 s[0:1], s[8:9], s[0:1]
	s_mov_b64 exec, s[0:1]
	s_cbranch_execz .LBB0_4306
	v_mov_b32_e32 v0, 0x240c0
	s_waitcnt vmcnt(0) lgkmcnt(0)
	ds_read_b32 v1, v0
	ds_read_b32 v2, v0 offset:4
	v_readlane_b32 s0, v254, 2
	s_waitcnt lgkmcnt(0)
	v_readfirstlane_b32 s1, v1
	v_readfirstlane_b32 s2, v2
	s_lshl_b32 s0, s0, 8
	s_add_i32 s0, s0, 0xc605400
	v_mov_b32_e32 v0, s0
	v_mov_b32_e32 v1, 1
	global_atomic_add v2, v0, v1, s[38:39] sc0
	v_cvt_f32_u32_e32 v0, s1
	v_rcp_f32_e32 v0, v0
	s_waitcnt vmcnt(0)
	v_cvt_f32_u32_e32 v1, v2
	v_add_f32_e32 v1, 0.5, v1
	v_mul_f32_e32 v1, v1, v0
	v_cvt_u32_f32_e32 v1, v1
	v_readfirstlane_b32 s5, v2
	v_readfirstlane_b32 s3, v1
	s_add_i32 s5, s5, 1
	s_add_i32 s3, s3, 1
	s_mul_i32 s4, s3, s1
	s_mul_i32 s3, s3, s2
	s_cmp_lg_u32 s5, s4
	s_cbranch_scc1 .Lfb_nl_25
	buffer_wbl2 sc1
	s_waitcnt vmcnt(0)
	v_mov_b32_e32 v0, 0xc607400
	v_mov_b32_e32 v1, 1
	global_atomic_add v0, v1, s[38:39]

.LBB0_4387:
	s_waitcnt vmcnt(0)
	s_waitcnt vmcnt(0)
	s_barrier
	s_mov_b64 s[6:7], exec
	v_readlane_b32 s0, v254, 3
	v_readlane_b32 s1, v254, 4
	s_and_b64 s[0:1], s[6:7], s[0:1]
	s_mov_b64 exec, s[0:1]
	s_cbranch_execz .LBB0_4439
	v_mov_b32_e32 v0, 0x240c0
	s_waitcnt vmcnt(0) lgkmcnt(0)
	ds_read_b32 v1, v0
	ds_read_b32 v2, v0 offset:4
	v_readlane_b32 s0, v254, 2
	s_waitcnt lgkmcnt(0)
	v_readfirstlane_b32 s1, v1
	v_readfirstlane_b32 s2, v2
	s_lshl_b32 s0, s0, 8
	s_add_i32 s0, s0, 0xc605400
	v_mov_b32_e32 v0, s0
	v_mov_b32_e32 v1, 1
	global_atomic_add v2, v0, v1, s[38:39] sc0
	v_cvt_f32_u32_e32 v0, s1
	v_rcp_f32_e32 v0, v0
	s_waitcnt vmcnt(0)
	v_cvt_f32_u32_e32 v1, v2
	v_add_f32_e32 v1, 0.5, v1
	v_mul_f32_e32 v1, v1, v0
	v_cvt_u32_f32_e32 v1, v1
	v_readfirstlane_b32 s5, v2
	v_readfirstlane_b32 s3, v1
	s_add_i32 s5, s5, 1
	s_add_i32 s3, s3, 1
	s_mul_i32 s4, s3, s1
	s_mul_i32 s3, s3, s2
	s_cmp_lg_u32 s5, s4
	s_cbranch_scc1 .Lfb_nl_27
	buffer_wbl2 sc1
	s_waitcnt vmcnt(0)
	v_mov_b32_e32 v0, 0xc607400
	v_mov_b32_e32 v1, 1
	global_atomic_add v0, v1, s[38:39]

.LBB0_4463:
	s_waitcnt vmcnt(0)
	s_barrier
	s_mov_b64 s[2:3], exec
	v_readlane_b32 s0, v254, 3
	v_readlane_b32 s1, v254, 4
	s_and_b64 s[0:1], s[2:3], s[0:1]
	s_mov_b64 exec, s[0:1]
	s_cbranch_execz .LBB0_4515
	v_mov_b32_e32 v0, 0x240c0
	s_waitcnt vmcnt(0) lgkmcnt(0)
	ds_read_b32 v1, v0
	ds_read_b32 v2, v0 offset:4
	v_readlane_b32 s0, v254, 2
	s_waitcnt lgkmcnt(0)
	v_readfirstlane_b32 s1, v1
	v_readfirstlane_b32 s4, v2
	s_lshl_b32 s0, s0, 8
	s_add_i32 s0, s0, 0xc605400
	v_mov_b32_e32 v0, s0
	v_mov_b32_e32 v1, 1
	global_atomic_add v2, v0, v1, s[38:39] sc0
	v_cvt_f32_u32_e32 v0, s1
	v_rcp_f32_e32 v0, v0
	s_waitcnt vmcnt(0)
	v_cvt_f32_u32_e32 v1, v2
	v_add_f32_e32 v1, 0.5, v1
	v_mul_f32_e32 v1, v1, v0
	v_cvt_u32_f32_e32 v1, v1
	v_readfirstlane_b32 s7, v2
	v_readfirstlane_b32 s5, v1
	s_add_i32 s7, s7, 1
	s_add_i32 s5, s5, 1
	s_mul_i32 s6, s5, s1
	s_mul_i32 s5, s5, s4
	s_cmp_lg_u32 s7, s6
	s_cbranch_scc1 .Lfb_nl_28
	buffer_wbl2 sc1
	s_waitcnt vmcnt(0)
	v_mov_b32_e32 v0, 0xc607400
	v_mov_b32_e32 v1, 1
	global_atomic_add v0, v1, s[38:39]

.Lfb_sp_28:
	global_load_dword v2, v0, s[38:39] sc1
	s_waitcnt vmcnt(0)
	v_readfirstlane_b32 s6, v2
	s_cmp_ge_u32 s6, s5
	s_cbranch_scc1 .Lfb_dn_28
	s_sleep 1
	s_add_i32 s7, s7, 1
	s_cmp_lt_u32 s7, 0x8000
	s_cbranch_scc1 .Lfb_sp_28
